# re-measure: s_sleep 2 in FFN-in GEMM load segments
# speedup vs baseline: 1.0400x; 1.0400x over previous
; template <class Epi, class Sched, bool ALIGN_EPI = false, bool SP2 = false>
; __device__ __forceinline__ void gemm_phase(PG8_LAS unsigned char* lds, const Gemm g, const Sched& S, const Epi& E) {
;     ...
;         const bool has_next = S.next(ui + 1, nxt);
;         const char* nA = has_next ? (const char*)g.A + (size_t)nxt.pm * tstepA : cA; const char* nB = has_next ? (const char*)g.Bt + (size_t)nxt.pn * tstepB : cB;
.LBB0_477:
	s_ashr_i32 s27, s26, 31
	s_lshl_b64 s[2:3], s[26:27], 15
	v_readlane_b32 s10, v255, 15
	s_add_u32 s28, s10, s2
	v_readlane_b32 s2, v255, 16
	s_addc_u32 s29, s2, s3
	s_ashr_i32 s25, s24, 31
	s_lshl_b64 s[2:3], s[24:25], 19
	s_add_u32 s30, s19, s2
	s_addc_u32 s31, s22, s3
	s_add_u32 s44, s34, 0x800000
	s_addc_u32 s45, s35, 0
	s_add_u32 s42, s34, 0xc00000
	s_addc_u32 s43, s35, 0
	s_add_i32 s61, 0, 0x10000
	s_and_b64 s[2:3], s[40:41], exec
	s_cselect_b32 s25, s29, s35
	s_cselect_b32 s27, s28, s34
	s_add_i32 s97, 0, 0x14000
	v_add_u32_e32 v142, s61, v97
	v_add_u32_e32 v143, s97, v97
	ds_read_b128 v[0:3], v142
	ds_read_b128 v[4:7], v142 offset:1024
	ds_read_b128 v[8:11], v142 offset:2048
	ds_read_b128 v[12:15], v142 offset:3072
	ds_read_b128 v[16:19], v143
	s_waitcnt lgkmcnt(0)
	ds_read_b128 v[20:23], v143 offset:1024
	ds_read_b128 v[24:27], v143 offset:2048
	ds_read_b128 v[28:31], v143 offset:3072
	s_and_b64 s[2:3], s[40:41], exec
	s_cselect_b32 s57, s31, s1
	s_cselect_b32 s58, s30, s0
	s_add_u32 s2, s34, 0x404000
	s_addc_u32 s3, s35, 0
	s_add_i32 s59, s23, 0xc000
	v_lshl_add_u64 v[64:65], s[2:3], 0, v[130:131]
	s_mov_b32 m0, s59
	s_add_i32 s60, s23, 0xe000
	ds_read_b128 v[32:35], v156
	ds_read_b128 v[36:39], v156 offset:1024
	ds_read_b128 v[40:43], v156 offset:2048
	ds_read_b128 v[44:47], v156 offset:3072
	ds_read_b128 v[48:51], v156 offset:4096
	ds_read_b128 v[52:55], v156 offset:5120
	ds_read_b128 v[56:59], v156 offset:6144
	ds_read_b128 v[60:63], v156 offset:7168
	global_load_lds_dwordx4 v[64:65], off
	v_lshl_add_u64 v[64:65], s[2:3], 0, v[134:135]
	s_mov_b32 m0, s60
	s_nop 0
	global_load_lds_dwordx4 v[64:65], off
	s_sleep 2
	s_waitcnt vmcnt(8)
	s_waitcnt lgkmcnt(0)
	s_barrier
	s_setprio 1
	s_waitcnt lgkmcnt(0)
	v_mfma_f32_16x16x32_bf16 v[88:91], v[0:3], v[56:59], 0
	v_mfma_f32_16x16x32_bf16 v[64:67], v[0:3], v[32:35], 0
	v_mfma_f32_16x16x32_bf16 v[68:71], v[8:11], v[32:35], 0
	v_mfma_f32_16x16x32_bf16 v[72:75], v[0:3], v[40:43], 0
	v_mfma_f32_16x16x32_bf16 v[76:79], v[8:11], v[40:43], 0
	v_mfma_f32_16x16x32_bf16 v[80:83], v[0:3], v[48:51], 0
	v_mfma_f32_16x16x32_bf16 v[84:87], v[8:11], v[48:51], 0
	v_mfma_f32_16x16x32_bf16 v[92:95], v[4:7], v[60:63], v[88:91]
	v_mfma_f32_16x16x32_bf16 v[88:91], v[8:11], v[56:59], 0
	v_mfma_f32_16x16x32_bf16 v[64:67], v[4:7], v[36:39], v[64:67]
	v_mfma_f32_16x16x32_bf16 v[68:71], v[12:15], v[36:39], v[68:71]
	v_mfma_f32_16x16x32_bf16 v[72:75], v[4:7], v[44:47], v[72:75]
	v_mfma_f32_16x16x32_bf16 v[76:79], v[12:15], v[44:47], v[76:79]
	v_mfma_f32_16x16x32_bf16 v[80:83], v[4:7], v[52:55], v[80:83]
	v_mfma_f32_16x16x32_bf16 v[84:87], v[12:15], v[52:55], v[84:87]
	v_mfma_f32_16x16x32_bf16 v[102:105], v[12:15], v[60:63], v[88:91]
	s_setprio 0
	s_setprio 1
	v_mfma_f32_16x16x32_bf16 v[88:91], v[16:19], v[32:35], 0
	v_mfma_f32_16x16x32_bf16 v[32:35], v[24:27], v[32:35], 0
	v_mfma_f32_16x16x32_bf16 v[110:113], v[20:23], v[36:39], v[88:91]
	v_mfma_f32_16x16x32_bf16 v[32:35], v[28:31], v[36:39], v[32:35]
	v_mfma_f32_16x16x32_bf16 v[36:39], v[16:19], v[40:43], 0
	v_mfma_f32_16x16x32_bf16 v[40:43], v[24:27], v[40:43], 0
	v_mfma_f32_16x16x32_bf16 v[36:39], v[20:23], v[44:47], v[36:39]
	v_mfma_f32_16x16x32_bf16 v[40:43], v[28:31], v[44:47], v[40:43]
	v_mfma_f32_16x16x32_bf16 v[44:47], v[16:19], v[48:51], 0
	v_mfma_f32_16x16x32_bf16 v[48:51], v[24:27], v[48:51], 0
	v_mfma_f32_16x16x32_bf16 v[44:47], v[20:23], v[52:55], v[44:47]
	v_mfma_f32_16x16x32_bf16 v[48:51], v[28:31], v[52:55], v[48:51]
	v_mfma_f32_16x16x32_bf16 v[52:55], v[16:19], v[56:59], 0
	v_mfma_f32_16x16x32_bf16 v[56:59], v[24:27], v[56:59], 0
	v_mfma_f32_16x16x32_bf16 v[52:55], v[20:23], v[60:63], v[52:55]
	v_mfma_f32_16x16x32_bf16 v[56:59], v[28:31], v[60:63], v[56:59]
	s_setprio 0
	s_barrier
	v_lshl_add_u64 v[154:155], s[0:1], 0, v[132:133]
	s_mov_b64 s[2:3], 0x100
	s_add_i32 s61, s61, s9
	v_lshl_add_u64 v[144:145], v[154:155], 0, s[2:3]
	s_mov_b32 m0, s61
	v_lshl_add_u64 v[178:179], s[0:1], 0, v[136:137]
	s_add_i32 s96, s61, 0x2000
	ds_read_b128 v[60:63], v156 offset:16384
	ds_read_b128 v[88:91], v156 offset:17408
	ds_read_b128 v[98:101], v156 offset:18432
	ds_read_b128 v[106:109], v156 offset:19456
	ds_read_b128 v[114:117], v156 offset:20480
	ds_read_b128 v[118:121], v156 offset:21504
	ds_read_b128 v[122:125], v156 offset:22528
	ds_read_b128 v[126:129], v156 offset:23552
	global_load_lds_dwordx4 v[144:145], off
	v_lshl_add_u64 v[144:145], v[178:179], 0, s[2:3]
	s_add_u32 s2, s0, 0x40100
	s_mov_b32 m0, s96
	s_addc_u32 s3, s1, 0
	s_add_i32 s97, s97, s9
	global_load_lds_dwordx4 v[144:145], off
	v_lshl_add_u64 v[144:145], s[2:3], 0, v[132:133]
	s_mov_b32 m0, s97
	s_add_i32 s98, s97, 0x2000
	global_load_lds_dwordx4 v[144:145], off
	v_lshl_add_u64 v[144:145], s[2:3], 0, v[136:137]
	s_mov_b32 m0, s98
	s_nop 0
	global_load_lds_dwordx4 v[144:145], off
	v_lshl_add_u64 v[144:145], s[44:45], 0, v[130:131]
	s_mov_b32 m0, s23
	s_nop 0
	global_load_lds_dwordx4 v[144:145], off
	v_lshl_add_u64 v[144:145], s[44:45], 0, v[134:135]
	s_mov_b32 m0, s39
	s_nop 0
	global_load_lds_dwordx4 v[144:145], off
	s_sleep 2
	s_waitcnt vmcnt(8)
	s_waitcnt lgkmcnt(0)
	s_barrier
	s_setprio 1
	s_waitcnt lgkmcnt(0)
	v_mfma_f32_16x16x32_bf16 v[144:147], v[0:3], v[60:63], 0
	v_mfma_f32_16x16x32_bf16 v[158:161], v[0:3], v[98:101], 0
	v_mfma_f32_16x16x32_bf16 v[166:169], v[0:3], v[114:117], 0
	v_mfma_f32_16x16x32_bf16 v[0:3], v[0:3], v[122:125], 0
	v_mfma_f32_16x16x32_bf16 v[146:149], v[4:7], v[88:91], v[144:147]
	v_mfma_f32_16x16x32_bf16 v[158:161], v[4:7], v[106:109], v[158:161]
	v_mfma_f32_16x16x32_bf16 v[166:169], v[4:7], v[118:121], v[166:169]
	v_mfma_f32_16x16x32_bf16 v[0:3], v[4:7], v[126:129], v[0:3]
	v_mfma_f32_16x16x32_bf16 v[4:7], v[8:11], v[122:125], 0
	v_mfma_f32_16x16x32_bf16 v[150:153], v[8:11], v[60:63], 0
	v_mfma_f32_16x16x32_bf16 v[162:165], v[8:11], v[98:101], 0
	v_mfma_f32_16x16x32_bf16 v[170:173], v[8:11], v[114:117], 0
	v_mfma_f32_16x16x32_bf16 v[4:7], v[12:15], v[126:129], v[4:7]
	v_mfma_f32_16x16x32_bf16 v[150:153], v[12:15], v[88:91], v[150:153]
	v_mfma_f32_16x16x32_bf16 v[162:165], v[12:15], v[106:109], v[162:165]
	v_mfma_f32_16x16x32_bf16 v[170:173], v[12:15], v[118:121], v[170:173]
	s_setprio 0
	s_setprio 1
	v_mfma_f32_16x16x32_bf16 v[8:11], v[16:19], v[60:63], 0
	v_mfma_f32_16x16x32_bf16 v[12:15], v[20:23], v[88:91], v[8:11]
	v_mfma_f32_16x16x32_bf16 v[8:11], v[24:27], v[60:63], 0
	v_mfma_f32_16x16x32_bf16 v[174:177], v[28:31], v[88:91], v[8:11]
	v_mfma_f32_16x16x32_bf16 v[8:11], v[16:19], v[98:101], 0
	v_mfma_f32_16x16x32_bf16 v[188:191], v[20:23], v[106:109], v[8:11]
	v_mfma_f32_16x16x32_bf16 v[8:11], v[24:27], v[98:101], 0
	v_mfma_f32_16x16x32_bf16 v[192:195], v[28:31], v[106:109], v[8:11]
	v_mfma_f32_16x16x32_bf16 v[8:11], v[16:19], v[114:117], 0
	v_mfma_f32_16x16x32_bf16 v[196:199], v[20:23], v[118:121], v[8:11]
	v_mfma_f32_16x16x32_bf16 v[8:11], v[24:27], v[114:117], 0
	v_mfma_f32_16x16x32_bf16 v[200:203], v[28:31], v[118:121], v[8:11]
	v_mfma_f32_16x16x32_bf16 v[8:11], v[16:19], v[122:125], 0
	v_mfma_f32_16x16x32_bf16 v[204:207], v[20:23], v[126:129], v[8:11]
	v_mfma_f32_16x16x32_bf16 v[8:11], v[24:27], v[122:125], 0
	v_mfma_f32_16x16x32_bf16 v[208:211], v[28:31], v[126:129], v[8:11]
	s_setprio 0
	s_barrier
	s_add_i32 s99, 0, 0x18000
	s_add_i32 vcc_hi, 0, 0x1c000
	v_add_u32_e32 v144, s99, v97
	v_add_u32_e32 v145, vcc_hi, v97
	s_nop 0
	ds_read_b128 v[8:11], v144
	ds_read_b128 v[20:23], v144 offset:1024
	ds_read_b128 v[28:31], v144 offset:2048
	ds_read_b128 v[212:215], v144 offset:3072
	ds_read_b128 v[216:219], v145
	ds_read_b128 v[220:223], v145 offset:1024
	ds_read_b128 v[234:237], v145 offset:2048
	ds_read_b128 v[238:241], v145 offset:3072
	s_add_u32 s2, s34, 0x804000
	s_addc_u32 s3, s35, 0
	s_mov_b32 m0, s46
	v_lshl_add_u64 v[60:61], s[2:3], 0, v[130:131]
	ds_read_b128 v[16:19], v156 offset:32768
	ds_read_b128 v[24:27], v156 offset:33792
	ds_read_b128 v[242:245], v156 offset:34816
	ds_read_b128 v[246:249], v156 offset:35840
	ds_read_b128 v[228:231], v156 offset:36864
	ds_read_b128 v[180:183], v156 offset:37888
	ds_read_b128 v[184:187], v156 offset:38912
	ds_read_b128 v[224:227], v156 offset:39936
	global_load_lds_dwordx4 v[60:61], off
	v_lshl_add_u64 v[60:61], s[2:3], 0, v[134:135]
	s_mov_b32 m0, s47
	s_nop 0
	global_load_lds_dwordx4 v[60:61], off
	s_sleep 2
	s_waitcnt vmcnt(8)
	s_waitcnt lgkmcnt(0)
	s_barrier
	s_setprio 1
	s_waitcnt lgkmcnt(0)
	v_mfma_f32_16x16x32_bf16 v[60:63], v[8:11], v[16:19], v[64:67]
	v_mfma_f32_16x16x32_bf16 v[122:125], v[20:23], v[24:27], v[60:63]
	v_mfma_f32_16x16x32_bf16 v[60:63], v[28:31], v[16:19], v[68:71]
	v_mfma_f32_16x16x32_bf16 v[114:117], v[212:215], v[24:27], v[60:63]
	v_mfma_f32_16x16x32_bf16 v[60:63], v[8:11], v[242:245], v[72:75]
	v_mfma_f32_16x16x32_bf16 v[106:109], v[20:23], v[246:249], v[60:63]
	v_mfma_f32_16x16x32_bf16 v[60:63], v[28:31], v[242:245], v[76:79]
	v_mfma_f32_16x16x32_bf16 v[98:101], v[212:215], v[246:249], v[60:63]
	v_mfma_f32_16x16x32_bf16 v[60:63], v[8:11], v[228:231], v[80:83]
	v_mfma_f32_16x16x32_bf16 v[88:91], v[20:23], v[180:183], v[60:63]
	v_mfma_f32_16x16x32_bf16 v[60:63], v[28:31], v[228:231], v[84:87]
	v_mfma_f32_16x16x32_bf16 v[80:83], v[212:215], v[180:183], v[60:63]
	v_mfma_f32_16x16x32_bf16 v[60:63], v[8:11], v[184:187], v[92:95]
	v_mfma_f32_16x16x32_bf16 v[72:75], v[20:23], v[224:227], v[60:63]
	v_mfma_f32_16x16x32_bf16 v[60:63], v[28:31], v[184:187], v[102:105]
	v_mfma_f32_16x16x32_bf16 v[60:63], v[212:215], v[224:227], v[60:63]
	s_setprio 0
	s_setprio 1
	v_mfma_f32_16x16x32_bf16 v[64:67], v[216:219], v[16:19], v[110:113]
	v_mfma_f32_16x16x32_bf16 v[16:19], v[234:237], v[16:19], v[32:35]
	v_mfma_f32_16x16x32_bf16 v[118:121], v[238:241], v[24:27], v[16:19]
	v_mfma_f32_16x16x32_bf16 v[16:19], v[216:219], v[242:245], v[36:39]
	v_mfma_f32_16x16x32_bf16 v[110:113], v[220:223], v[246:249], v[16:19]
	v_mfma_f32_16x16x32_bf16 v[16:19], v[234:237], v[242:245], v[40:43]
	v_mfma_f32_16x16x32_bf16 v[102:105], v[238:241], v[246:249], v[16:19]
	v_mfma_f32_16x16x32_bf16 v[16:19], v[216:219], v[228:231], v[44:47]
	v_mfma_f32_16x16x32_bf16 v[92:95], v[220:223], v[180:183], v[16:19]
	v_mfma_f32_16x16x32_bf16 v[16:19], v[234:237], v[228:231], v[48:51]
	v_mfma_f32_16x16x32_bf16 v[84:87], v[238:241], v[180:183], v[16:19]
	v_mfma_f32_16x16x32_bf16 v[16:19], v[216:219], v[184:187], v[52:55]
	v_mfma_f32_16x16x32_bf16 v[76:79], v[220:223], v[224:227], v[16:19]
	v_mfma_f32_16x16x32_bf16 v[16:19], v[234:237], v[184:187], v[56:59]
	v_mfma_f32_16x16x32_bf16 v[126:129], v[220:223], v[24:27], v[64:67]
	v_mfma_f32_16x16x32_bf16 v[68:71], v[238:241], v[224:227], v[16:19]
	s_setprio 0
	s_barrier
; template <class Epi, class Sched, bool ALIGN_EPI = false, bool SP2 = false>
; __device__ __forceinline__ void gemm_phase(PG8_LAS unsigned char* lds, const Gemm g, const Sched& S, const Epi& E) {
;     ...
;         for (int t = (Epi::PEEL ? 2 : 0); t < nt; t += 2) {
;             const bool last = (t == nt - 2);
;             const char* a1 = cA + (size_t)(t + 1) * kstepA;
;             const char* a2 = last ? nA : cA + (size_t)(t + 2) * kstepA; const char* b2 = last ? nB : cB + (size_t)(t + 2) * kstepB;
;             const char* a3 = a2 + kstepA; const char* b3 = b2 + kstepB;
	s_mov_b64 s[2:3], 0x180
	s_add_i32 s99, s99, s9
	s_nop 1
	v_lshl_add_u64 v[16:17], v[154:155], 0, s[2:3]
	s_mov_b32 m0, s99
	s_add_i32 vcc_lo, s99, 0x2000
	ds_read_b128 v[36:39], v156 offset:49152
	ds_read_b128 v[44:47], v156 offset:50176
	ds_read_b128 v[180:183], v156 offset:51200
	ds_read_b128 v[184:187], v156 offset:52224
	ds_read_b128 v[224:227], v156 offset:53248
	ds_read_b128 v[228:231], v156 offset:54272
	ds_read_b128 v[242:245], v156 offset:55296
	ds_read_b128 v[246:249], v156 offset:56320
	global_load_lds_dwordx4 v[16:17], off
	v_lshl_add_u64 v[16:17], v[178:179], 0, s[2:3]
	s_add_u32 s2, s0, 0x40180
	s_mov_b32 m0, vcc_lo
	s_addc_u32 s3, s1, 0
	s_add_i32 vcc_hi, vcc_hi, s9
	global_load_lds_dwordx4 v[16:17], off
	v_lshl_add_u64 v[16:17], s[2:3], 0, v[132:133]
	s_mov_b32 m0, vcc_hi
	s_add_i32 s38, vcc_hi, 0x2000
	global_load_lds_dwordx4 v[16:17], off
	v_lshl_add_u64 v[16:17], s[2:3], 0, v[136:137]
	s_mov_b32 m0, s38
	s_nop 0
	global_load_lds_dwordx4 v[16:17], off
	v_lshl_add_u64 v[16:17], s[42:43], 0, v[130:131]
	s_mov_b32 m0, s49
	s_nop 0
	global_load_lds_dwordx4 v[16:17], off
	v_lshl_add_u64 v[16:17], s[42:43], 0, v[134:135]
	s_mov_b32 m0, s50
	s_nop 0
	global_load_lds_dwordx4 v[16:17], off
	s_sleep 2
	s_waitcnt vmcnt(8)
	s_waitcnt lgkmcnt(0)
	s_barrier
	s_setprio 1
	s_waitcnt lgkmcnt(0)
	v_mfma_f32_16x16x32_bf16 v[16:19], v[8:11], v[36:39], v[146:149]
	v_mfma_f32_16x16x32_bf16 v[56:59], v[20:23], v[44:47], v[16:19]
	v_mfma_f32_16x16x32_bf16 v[16:19], v[28:31], v[36:39], v[150:153]
	v_mfma_f32_16x16x32_bf16 v[48:51], v[212:215], v[44:47], v[16:19]
	v_mfma_f32_16x16x32_bf16 v[16:19], v[8:11], v[180:183], v[158:161]
	v_mfma_f32_16x16x32_bf16 v[40:43], v[20:23], v[184:187], v[16:19]
	v_mfma_f32_16x16x32_bf16 v[16:19], v[28:31], v[180:183], v[162:165]
	v_mfma_f32_16x16x32_bf16 v[32:35], v[212:215], v[184:187], v[16:19]
	v_mfma_f32_16x16x32_bf16 v[16:19], v[8:11], v[224:227], v[166:169]
	v_mfma_f32_16x16x32_bf16 v[0:3], v[8:11], v[242:245], v[0:3]
	v_mfma_f32_16x16x32_bf16 v[24:27], v[20:23], v[228:231], v[16:19]
	v_mfma_f32_16x16x32_bf16 v[16:19], v[28:31], v[224:227], v[170:173]
	v_mfma_f32_16x16x32_bf16 v[8:11], v[20:23], v[246:249], v[0:3]
	v_mfma_f32_16x16x32_bf16 v[0:3], v[28:31], v[242:245], v[4:7]
	v_mfma_f32_16x16x32_bf16 v[16:19], v[212:215], v[228:231], v[16:19]
	v_mfma_f32_16x16x32_bf16 v[0:3], v[212:215], v[246:249], v[0:3]
	s_setprio 0
	s_setprio 1
	v_mfma_f32_16x16x32_bf16 v[4:7], v[216:219], v[36:39], v[12:15]
	v_mfma_f32_16x16x32_bf16 v[64:67], v[220:223], v[44:47], v[4:7]
	v_mfma_f32_16x16x32_bf16 v[4:7], v[234:237], v[36:39], v[174:177]
	v_mfma_f32_16x16x32_bf16 v[52:55], v[238:241], v[44:47], v[4:7]
	v_mfma_f32_16x16x32_bf16 v[4:7], v[216:219], v[180:183], v[188:191]
	v_mfma_f32_16x16x32_bf16 v[44:47], v[220:223], v[184:187], v[4:7]
	v_mfma_f32_16x16x32_bf16 v[4:7], v[234:237], v[180:183], v[192:195]
	v_mfma_f32_16x16x32_bf16 v[36:39], v[238:241], v[184:187], v[4:7]
	v_mfma_f32_16x16x32_bf16 v[4:7], v[216:219], v[224:227], v[196:199]
	v_mfma_f32_16x16x32_bf16 v[28:31], v[220:223], v[228:231], v[4:7]
	v_mfma_f32_16x16x32_bf16 v[4:7], v[234:237], v[224:227], v[200:203]
	v_mfma_f32_16x16x32_bf16 v[20:23], v[238:241], v[228:231], v[4:7]
	v_mfma_f32_16x16x32_bf16 v[4:7], v[216:219], v[242:245], v[204:207]
	v_mfma_f32_16x16x32_bf16 v[12:15], v[220:223], v[246:249], v[4:7]
	v_mfma_f32_16x16x32_bf16 v[4:7], v[234:237], v[242:245], v[208:211]
	v_mfma_f32_16x16x32_bf16 v[4:7], v[238:241], v[246:249], v[4:7]
	s_setprio 0
	s_barrier
	s_add_u32 s3, s0, 0x200
	s_addc_u32 s2, s1, 0
	s_add_u32 s0, s34, 0xc04000
	s_addc_u32 s1, s35, 0
	s_mov_b32 s18, 0
.LBB0_478:
	ds_read_b128 v[146:149], v142
	ds_read_b128 v[150:153], v142 offset:1024
	ds_read_b128 v[158:161], v142 offset:2048
	ds_read_b128 v[162:165], v142 offset:3072
	ds_read_b128 v[166:169], v143
	ds_read_b128 v[170:173], v143 offset:1024
	ds_read_b128 v[174:177], v143 offset:2048
	ds_read_b128 v[180:183], v143 offset:3072
	s_add_u32 s10, s0, 0x3fc000
	s_addc_u32 s11, s1, 0
	s_cmp_eq_u32 s18, 12
	s_cselect_b32 s44, s27, s10
	s_cselect_b32 s45, s25, s11
	s_cselect_b32 s42, s58, s3
	s_cselect_b32 s43, s57, s2
	s_add_u32 s34, s44, 0x400000
	s_addc_u32 s35, s45, 0
	s_mov_b32 m0, s59
	v_lshl_add_u64 v[154:155], s[0:1], 0, v[140:141]
	ds_read_b128 v[184:187], v156
	ds_read_b128 v[188:191], v156 offset:1024
	ds_read_b128 v[192:195], v156 offset:2048
	ds_read_b128 v[196:199], v156 offset:3072
	ds_read_b128 v[200:203], v156 offset:4096
	ds_read_b128 v[204:207], v156 offset:5120
	ds_read_b128 v[208:211], v156 offset:6144
	ds_read_b128 v[212:215], v156 offset:7168
	global_load_lds_dwordx4 v[154:155], off
	v_lshl_add_u64 v[154:155], s[0:1], 0, v[138:139]
	s_mov_b32 m0, s60
	s_nop 0
	global_load_lds_dwordx4 v[154:155], off
	s_sleep 2
	s_waitcnt vmcnt(8)
	s_waitcnt lgkmcnt(0)
	s_barrier
	s_setprio 1
	s_waitcnt lgkmcnt(0)
	v_mfma_f32_16x16x32_bf16 v[122:125], v[146:149], v[184:187], v[122:125]
	v_mfma_f32_16x16x32_bf16 v[114:117], v[158:161], v[184:187], v[114:117]
	v_mfma_f32_16x16x32_bf16 v[106:109], v[146:149], v[192:195], v[106:109]
	v_mfma_f32_16x16x32_bf16 v[98:101], v[158:161], v[192:195], v[98:101]
	v_mfma_f32_16x16x32_bf16 v[88:91], v[146:149], v[200:203], v[88:91]
	v_mfma_f32_16x16x32_bf16 v[80:83], v[158:161], v[200:203], v[80:83]
	v_mfma_f32_16x16x32_bf16 v[72:75], v[146:149], v[208:211], v[72:75]
	v_mfma_f32_16x16x32_bf16 v[60:63], v[158:161], v[208:211], v[60:63]
	v_mfma_f32_16x16x32_bf16 v[122:125], v[150:153], v[188:191], v[122:125]
	v_mfma_f32_16x16x32_bf16 v[114:117], v[162:165], v[188:191], v[114:117]
	v_mfma_f32_16x16x32_bf16 v[106:109], v[150:153], v[196:199], v[106:109]
	v_mfma_f32_16x16x32_bf16 v[98:101], v[162:165], v[196:199], v[98:101]
	v_mfma_f32_16x16x32_bf16 v[88:91], v[150:153], v[204:207], v[88:91]
	v_mfma_f32_16x16x32_bf16 v[80:83], v[162:165], v[204:207], v[80:83]
	v_mfma_f32_16x16x32_bf16 v[72:75], v[150:153], v[212:215], v[72:75]
	v_mfma_f32_16x16x32_bf16 v[60:63], v[162:165], v[212:215], v[60:63]
	s_setprio 0
	s_setprio 1
	v_mfma_f32_16x16x32_bf16 v[126:129], v[166:169], v[184:187], v[126:129]
	v_mfma_f32_16x16x32_bf16 v[118:121], v[174:177], v[184:187], v[118:121]
	v_mfma_f32_16x16x32_bf16 v[110:113], v[166:169], v[192:195], v[110:113]
	v_mfma_f32_16x16x32_bf16 v[102:105], v[174:177], v[192:195], v[102:105]
	v_mfma_f32_16x16x32_bf16 v[92:95], v[166:169], v[200:203], v[92:95]
	v_mfma_f32_16x16x32_bf16 v[84:87], v[174:177], v[200:203], v[84:87]
	v_mfma_f32_16x16x32_bf16 v[76:79], v[166:169], v[208:211], v[76:79]
	v_mfma_f32_16x16x32_bf16 v[68:71], v[174:177], v[208:211], v[68:71]
	v_mfma_f32_16x16x32_bf16 v[126:129], v[170:173], v[188:191], v[126:129]
	v_mfma_f32_16x16x32_bf16 v[118:121], v[180:183], v[188:191], v[118:121]
	v_mfma_f32_16x16x32_bf16 v[110:113], v[170:173], v[196:199], v[110:113]
	v_mfma_f32_16x16x32_bf16 v[102:105], v[180:183], v[196:199], v[102:105]
	v_mfma_f32_16x16x32_bf16 v[92:95], v[170:173], v[204:207], v[92:95]
	v_mfma_f32_16x16x32_bf16 v[84:87], v[180:183], v[204:207], v[84:87]
	v_mfma_f32_16x16x32_bf16 v[76:79], v[170:173], v[212:215], v[76:79]
	v_mfma_f32_16x16x32_bf16 v[68:71], v[180:183], v[212:215], v[68:71]
	s_setprio 0
	s_barrier
	s_mov_b32 m0, s61
	v_lshl_add_u64 v[154:155], s[42:43], 0, v[132:133]
	s_add_u32 s10, s42, 0x40000
	ds_read_b128 v[184:187], v156 offset:16384
	ds_read_b128 v[188:191], v156 offset:17408
	ds_read_b128 v[192:195], v156 offset:18432
	ds_read_b128 v[196:199], v156 offset:19456
	ds_read_b128 v[200:203], v156 offset:20480
	ds_read_b128 v[204:207], v156 offset:21504
	ds_read_b128 v[208:211], v156 offset:22528
	ds_read_b128 v[212:215], v156 offset:23552
	global_load_lds_dwordx4 v[154:155], off
	v_lshl_add_u64 v[178:179], s[42:43], 0, v[136:137]
	s_mov_b32 m0, s96
	s_addc_u32 s11, s43, 0
	global_load_lds_dwordx4 v[178:179], off
	v_lshl_add_u64 v[216:217], s[10:11], 0, v[132:133]
	s_mov_b32 m0, s97
	s_nop 0
	global_load_lds_dwordx4 v[216:217], off
	v_lshl_add_u64 v[216:217], s[10:11], 0, v[136:137]
	s_mov_b32 m0, s98
	s_nop 0
	global_load_lds_dwordx4 v[216:217], off
	v_lshl_add_u64 v[216:217], s[44:45], 0, v[130:131]
	s_mov_b32 m0, s23
	s_nop 0
	global_load_lds_dwordx4 v[216:217], off
	v_lshl_add_u64 v[216:217], s[44:45], 0, v[134:135]
	s_mov_b32 m0, s39
	s_nop 0
	global_load_lds_dwordx4 v[216:217], off
	s_sleep 2
	s_waitcnt vmcnt(8)
	s_waitcnt lgkmcnt(0)
	s_barrier
	s_setprio 1
	s_waitcnt lgkmcnt(0)
	v_mfma_f32_16x16x32_bf16 v[56:59], v[146:149], v[184:187], v[56:59]
	v_mfma_f32_16x16x32_bf16 v[48:51], v[158:161], v[184:187], v[48:51]
	v_mfma_f32_16x16x32_bf16 v[40:43], v[146:149], v[192:195], v[40:43]
	v_mfma_f32_16x16x32_bf16 v[32:35], v[158:161], v[192:195], v[32:35]
	v_mfma_f32_16x16x32_bf16 v[24:27], v[146:149], v[200:203], v[24:27]
	v_mfma_f32_16x16x32_bf16 v[16:19], v[158:161], v[200:203], v[16:19]
	v_mfma_f32_16x16x32_bf16 v[8:11], v[146:149], v[208:211], v[8:11]
	v_mfma_f32_16x16x32_bf16 v[0:3], v[158:161], v[208:211], v[0:3]
	v_mfma_f32_16x16x32_bf16 v[56:59], v[150:153], v[188:191], v[56:59]
	v_mfma_f32_16x16x32_bf16 v[48:51], v[162:165], v[188:191], v[48:51]
	v_mfma_f32_16x16x32_bf16 v[40:43], v[150:153], v[196:199], v[40:43]
	v_mfma_f32_16x16x32_bf16 v[32:35], v[162:165], v[196:199], v[32:35]
	v_mfma_f32_16x16x32_bf16 v[24:27], v[150:153], v[204:207], v[24:27]
	v_mfma_f32_16x16x32_bf16 v[16:19], v[162:165], v[204:207], v[16:19]
	v_mfma_f32_16x16x32_bf16 v[8:11], v[150:153], v[212:215], v[8:11]
	v_mfma_f32_16x16x32_bf16 v[0:3], v[162:165], v[212:215], v[0:3]
	s_setprio 0
	s_setprio 1
	v_mfma_f32_16x16x32_bf16 v[64:67], v[166:169], v[184:187], v[64:67]
	v_mfma_f32_16x16x32_bf16 v[52:55], v[174:177], v[184:187], v[52:55]
	v_mfma_f32_16x16x32_bf16 v[44:47], v[166:169], v[192:195], v[44:47]
	v_mfma_f32_16x16x32_bf16 v[36:39], v[174:177], v[192:195], v[36:39]
	v_mfma_f32_16x16x32_bf16 v[28:31], v[166:169], v[200:203], v[28:31]
	v_mfma_f32_16x16x32_bf16 v[20:23], v[174:177], v[200:203], v[20:23]
	v_mfma_f32_16x16x32_bf16 v[12:15], v[166:169], v[208:211], v[12:15]
	v_mfma_f32_16x16x32_bf16 v[4:7], v[174:177], v[208:211], v[4:7]
	v_mfma_f32_16x16x32_bf16 v[64:67], v[170:173], v[188:191], v[64:67]
	v_mfma_f32_16x16x32_bf16 v[52:55], v[180:183], v[188:191], v[52:55]
	v_mfma_f32_16x16x32_bf16 v[44:47], v[170:173], v[196:199], v[44:47]
	v_mfma_f32_16x16x32_bf16 v[36:39], v[180:183], v[196:199], v[36:39]
	v_mfma_f32_16x16x32_bf16 v[28:31], v[170:173], v[204:207], v[28:31]
	v_mfma_f32_16x16x32_bf16 v[20:23], v[180:183], v[204:207], v[20:23]
	v_mfma_f32_16x16x32_bf16 v[12:15], v[170:173], v[212:215], v[12:15]
	v_mfma_f32_16x16x32_bf16 v[4:7], v[180:183], v[212:215], v[4:7]
	s_setprio 0
	s_barrier
	ds_read_b128 v[146:149], v144
	ds_read_b128 v[150:153], v144 offset:1024
	ds_read_b128 v[158:161], v144 offset:2048
	ds_read_b128 v[162:165], v144 offset:3072
	ds_read_b128 v[166:169], v145
	ds_read_b128 v[170:173], v145 offset:1024
	ds_read_b128 v[174:177], v145 offset:2048
	ds_read_b128 v[180:183], v145 offset:3072
	s_add_u32 s10, s44, 0x4000
	s_addc_u32 s11, s45, 0
	s_mov_b32 m0, s46
	v_lshl_add_u64 v[216:217], s[10:11], 0, v[130:131]
	ds_read_b128 v[184:187], v156 offset:32768
	ds_read_b128 v[188:191], v156 offset:33792
	ds_read_b128 v[192:195], v156 offset:34816
	ds_read_b128 v[196:199], v156 offset:35840
	ds_read_b128 v[200:203], v156 offset:36864
	ds_read_b128 v[204:207], v156 offset:37888
	ds_read_b128 v[208:211], v156 offset:38912
	ds_read_b128 v[212:215], v156 offset:39936
	global_load_lds_dwordx4 v[216:217], off
	v_lshl_add_u64 v[216:217], s[10:11], 0, v[134:135]
	s_mov_b32 m0, s47
	s_nop 0
	global_load_lds_dwordx4 v[216:217], off
	s_sleep 2
	s_waitcnt vmcnt(8)
	s_waitcnt lgkmcnt(0)
	s_barrier
	s_setprio 1
	s_waitcnt lgkmcnt(0)
	v_mfma_f32_16x16x32_bf16 v[122:125], v[146:149], v[184:187], v[122:125]
	v_mfma_f32_16x16x32_bf16 v[114:117], v[158:161], v[184:187], v[114:117]
	v_mfma_f32_16x16x32_bf16 v[106:109], v[146:149], v[192:195], v[106:109]
	v_mfma_f32_16x16x32_bf16 v[98:101], v[158:161], v[192:195], v[98:101]
	v_mfma_f32_16x16x32_bf16 v[88:91], v[146:149], v[200:203], v[88:91]
	v_mfma_f32_16x16x32_bf16 v[80:83], v[158:161], v[200:203], v[80:83]
	v_mfma_f32_16x16x32_bf16 v[72:75], v[146:149], v[208:211], v[72:75]
	v_mfma_f32_16x16x32_bf16 v[60:63], v[158:161], v[208:211], v[60:63]
	v_mfma_f32_16x16x32_bf16 v[122:125], v[150:153], v[188:191], v[122:125]
	v_mfma_f32_16x16x32_bf16 v[114:117], v[162:165], v[188:191], v[114:117]
	v_mfma_f32_16x16x32_bf16 v[106:109], v[150:153], v[196:199], v[106:109]
	v_mfma_f32_16x16x32_bf16 v[98:101], v[162:165], v[196:199], v[98:101]
	v_mfma_f32_16x16x32_bf16 v[88:91], v[150:153], v[204:207], v[88:91]
	v_mfma_f32_16x16x32_bf16 v[80:83], v[162:165], v[204:207], v[80:83]
	v_mfma_f32_16x16x32_bf16 v[72:75], v[150:153], v[212:215], v[72:75]
	v_mfma_f32_16x16x32_bf16 v[60:63], v[162:165], v[212:215], v[60:63]
	s_setprio 0
	s_setprio 1
	v_mfma_f32_16x16x32_bf16 v[126:129], v[166:169], v[184:187], v[126:129]
	v_mfma_f32_16x16x32_bf16 v[118:121], v[174:177], v[184:187], v[118:121]
	v_mfma_f32_16x16x32_bf16 v[110:113], v[166:169], v[192:195], v[110:113]
	v_mfma_f32_16x16x32_bf16 v[102:105], v[174:177], v[192:195], v[102:105]
	v_mfma_f32_16x16x32_bf16 v[92:95], v[166:169], v[200:203], v[92:95]
	v_mfma_f32_16x16x32_bf16 v[84:87], v[174:177], v[200:203], v[84:87]
	v_mfma_f32_16x16x32_bf16 v[76:79], v[166:169], v[208:211], v[76:79]
	v_mfma_f32_16x16x32_bf16 v[68:71], v[174:177], v[208:211], v[68:71]
	v_mfma_f32_16x16x32_bf16 v[126:129], v[170:173], v[188:191], v[126:129]
	v_mfma_f32_16x16x32_bf16 v[118:121], v[180:183], v[188:191], v[118:121]
	v_mfma_f32_16x16x32_bf16 v[110:113], v[170:173], v[196:199], v[110:113]
	v_mfma_f32_16x16x32_bf16 v[102:105], v[180:183], v[196:199], v[102:105]
	v_mfma_f32_16x16x32_bf16 v[92:95], v[170:173], v[204:207], v[92:95]
	v_mfma_f32_16x16x32_bf16 v[84:87], v[180:183], v[204:207], v[84:87]
	v_mfma_f32_16x16x32_bf16 v[76:79], v[170:173], v[212:215], v[76:79]
	v_mfma_f32_16x16x32_bf16 v[68:71], v[180:183], v[212:215], v[68:71]
	s_setprio 0
	s_barrier
; #define PG8_BAR __builtin_amdgcn_s_barrier()
; template <class Epi, class Sched, bool ALIGN_EPI = false, bool SP2 = false>
; __device__ __forceinline__ void gemm_phase(PG8_LAS unsigned char* lds, const Gemm g, const Sched& S, const Epi& E) {
;     ...
;             PG8_ITER(8);
;         }
;     ...
;         if constexpr (ALIGN_EPI) { if (wr == 0) PG8_BAR; }
	s_mov_b32 m0, s99
	v_lshl_add_u64 v[154:155], v[154:155], 0, s[36:37]
	s_add_u32 s10, s42, 0x40080
	ds_read_b128 v[184:187], v156 offset:49152
	ds_read_b128 v[188:191], v156 offset:50176
	ds_read_b128 v[192:195], v156 offset:51200
	ds_read_b128 v[196:199], v156 offset:52224
	ds_read_b128 v[200:203], v156 offset:53248
	ds_read_b128 v[204:207], v156 offset:54272
	ds_read_b128 v[208:211], v156 offset:55296
	ds_read_b128 v[212:215], v156 offset:56320
	global_load_lds_dwordx4 v[154:155], off
	v_lshl_add_u64 v[154:155], v[178:179], 0, s[36:37]
	s_mov_b32 m0, vcc_lo
	s_addc_u32 s11, s43, 0
	global_load_lds_dwordx4 v[154:155], off
	v_lshl_add_u64 v[154:155], s[10:11], 0, v[132:133]
	s_mov_b32 m0, vcc_hi
	s_nop 0
	global_load_lds_dwordx4 v[154:155], off
	v_lshl_add_u64 v[154:155], s[10:11], 0, v[136:137]
	s_mov_b32 m0, s38
	s_nop 0
	global_load_lds_dwordx4 v[154:155], off
	v_lshl_add_u64 v[154:155], s[34:35], 0, v[130:131]
	s_mov_b32 m0, s49
	s_nop 0
	global_load_lds_dwordx4 v[154:155], off
	v_lshl_add_u64 v[154:155], s[34:35], 0, v[134:135]
	s_mov_b32 m0, s50
	s_nop 0
	global_load_lds_dwordx4 v[154:155], off
	s_sleep 2
	s_waitcnt vmcnt(8)
	s_waitcnt lgkmcnt(0)
	s_barrier
	s_setprio 1
	s_waitcnt lgkmcnt(0)
	v_mfma_f32_16x16x32_bf16 v[56:59], v[146:149], v[184:187], v[56:59]
	v_mfma_f32_16x16x32_bf16 v[48:51], v[158:161], v[184:187], v[48:51]
	v_mfma_f32_16x16x32_bf16 v[40:43], v[146:149], v[192:195], v[40:43]
	v_mfma_f32_16x16x32_bf16 v[32:35], v[158:161], v[192:195], v[32:35]
	v_mfma_f32_16x16x32_bf16 v[24:27], v[146:149], v[200:203], v[24:27]
	v_mfma_f32_16x16x32_bf16 v[16:19], v[158:161], v[200:203], v[16:19]
	v_mfma_f32_16x16x32_bf16 v[8:11], v[146:149], v[208:211], v[8:11]
	v_mfma_f32_16x16x32_bf16 v[0:3], v[158:161], v[208:211], v[0:3]
	v_mfma_f32_16x16x32_bf16 v[56:59], v[150:153], v[188:191], v[56:59]
	v_mfma_f32_16x16x32_bf16 v[48:51], v[162:165], v[188:191], v[48:51]
	v_mfma_f32_16x16x32_bf16 v[40:43], v[150:153], v[196:199], v[40:43]
	v_mfma_f32_16x16x32_bf16 v[32:35], v[162:165], v[196:199], v[32:35]
	v_mfma_f32_16x16x32_bf16 v[24:27], v[150:153], v[204:207], v[24:27]
	v_mfma_f32_16x16x32_bf16 v[16:19], v[162:165], v[204:207], v[16:19]
	v_mfma_f32_16x16x32_bf16 v[8:11], v[150:153], v[212:215], v[8:11]
	v_mfma_f32_16x16x32_bf16 v[0:3], v[162:165], v[212:215], v[0:3]
	s_setprio 0
	s_setprio 1
	v_mfma_f32_16x16x32_bf16 v[64:67], v[166:169], v[184:187], v[64:67]
	v_mfma_f32_16x16x32_bf16 v[52:55], v[174:177], v[184:187], v[52:55]
	v_mfma_f32_16x16x32_bf16 v[44:47], v[166:169], v[192:195], v[44:47]
	v_mfma_f32_16x16x32_bf16 v[36:39], v[174:177], v[192:195], v[36:39]
	v_mfma_f32_16x16x32_bf16 v[28:31], v[166:169], v[200:203], v[28:31]
	v_mfma_f32_16x16x32_bf16 v[20:23], v[174:177], v[200:203], v[20:23]
	v_mfma_f32_16x16x32_bf16 v[12:15], v[166:169], v[208:211], v[12:15]
	v_mfma_f32_16x16x32_bf16 v[4:7], v[174:177], v[208:211], v[4:7]
	v_mfma_f32_16x16x32_bf16 v[64:67], v[170:173], v[188:191], v[64:67]
	v_mfma_f32_16x16x32_bf16 v[52:55], v[180:183], v[188:191], v[52:55]
	v_mfma_f32_16x16x32_bf16 v[44:47], v[170:173], v[196:199], v[44:47]
	v_mfma_f32_16x16x32_bf16 v[36:39], v[180:183], v[196:199], v[36:39]
	v_mfma_f32_16x16x32_bf16 v[28:31], v[170:173], v[204:207], v[28:31]
	v_mfma_f32_16x16x32_bf16 v[20:23], v[180:183], v[204:207], v[20:23]
	v_mfma_f32_16x16x32_bf16 v[12:15], v[170:173], v[212:215], v[12:15]
	v_mfma_f32_16x16x32_bf16 v[4:7], v[180:183], v[212:215], v[4:7]
	s_setprio 0
	s_barrier
	s_add_i32 s18, s18, 2
	s_add_u32 s3, s3, 0x100
	s_addc_u32 s2, s2, 0
	s_add_u32 s0, s0, 0x800000
	s_addc_u32 s1, s1, 0
	s_cmp_gt_u32 s18, 13
	s_cbranch_scc0 .LBB0_478
	s_and_b64 vcc, exec, s[16:17]
	s_cbranch_vccz .LBB0_481
	s_barrier
